# P1 context row (waves 0-3): gain/scale/shift loads of chunks 1..15 in three batches of five (two in flight) instead of 15 serial round trips; on top of v115
# speedup vs baseline: 1.0120x; 1.0120x over previous
.LBB0_217:
	s_cmpk_lt_u32 s95, 0x100
	s_cbranch_scc0 .LBB0_219
	s_lshl_b32 s0, s62, 2
	s_add_i32 s1, s0, s92
	s_or_b32 s0, s92, s0
	s_add_i32 s2, s1, 0x2000
	s_ashr_i32 s1, s0, 31
	s_lshl_b64 s[0:1], s[0:1], 14
	s_add_u32 s0, s20, s0
	s_addc_u32 s1, s21, s1
	v_lshlrev_b32_e32 v66, 4, v178
	v_mov_b32_e32 v67, 0
	s_movk_i32 s6, 0x2000
	v_lshl_add_u64 v[2:3], s[0:1], 0, v[66:67]
	v_add_co_u32_e32 v4, vcc, s6, v2
	global_load_dwordx4 v[62:65], v66, s[0:1] nt
	global_load_dwordx4 v[58:61], v66, s[0:1] offset:1024 nt
	global_load_dwordx4 v[54:57], v66, s[0:1] offset:2048 nt
	global_load_dwordx4 v[46:49], v66, s[0:1] offset:3072 nt
	v_addc_co_u32_e32 v5, vcc, 0, v3, vcc
	global_load_dwordx4 v[50:53], v[4:5], off offset:-4096 nt
	s_movk_i32 s5, 0x1000
	s_waitcnt vmcnt(11)
	v_add_co_u32_e32 v6, vcc, s5, v2
	s_movk_i32 s4, 0x3000
	s_nop 0
	v_addc_co_u32_e32 v7, vcc, 0, v3, vcc
	global_load_dwordx4 v[42:45], v[6:7], off offset:1024 nt
	global_load_dwordx4 v[38:41], v[6:7], off offset:2048 nt
	global_load_dwordx4 v[34:37], v[6:7], off offset:3072 nt
	global_load_dwordx4 v[30:33], v[4:5], off nt
	global_load_dwordx4 v[22:25], v[4:5], off offset:1024 nt
	global_load_dwordx4 v[18:21], v[4:5], off offset:2048 nt
	s_nop 0
	global_load_dwordx4 v[6:9], v[4:5], off offset:3072 nt
	s_waitcnt vmcnt(17)
	v_add_co_u32_e32 v10, vcc, s4, v2
	s_mov_b32 s0, 0x161000
	s_nop 0
	v_addc_co_u32_e32 v11, vcc, 0, v3, vcc
	global_load_dwordx4 v[2:5], v[10:11], off nt
	global_load_dwordx4 v[78:81], v66, s[28:29]
	global_load_dwordx4 v[26:29], v[10:11], off offset:1024 nt
	global_load_dwordx4 v[14:17], v[10:11], off offset:2048 nt
	s_nop 0
	global_load_dwordx4 v[10:13], v[10:11], off offset:3072 nt
	s_ashr_i32 s3, s2, 31
	s_mov_b64 s[12:13], 0x164000
	s_waitcnt vmcnt(16)
	v_mul_f32_e32 v1, v63, v63
	v_mul_f32_e32 v68, v65, v65
	s_waitcnt vmcnt(15)
	v_mul_f32_e32 v69, v59, v59
	v_mul_f32_e32 v70, v61, v61
	s_waitcnt vmcnt(14)
	v_mul_f32_e32 v71, v55, v55
	v_mul_f32_e32 v72, v57, v57
	v_fmac_f32_e32 v1, v62, v62
	v_fmac_f32_e32 v68, v64, v64
	v_fmac_f32_e32 v69, v58, v58
	v_fmac_f32_e32 v70, v60, v60
	s_waitcnt vmcnt(13)
	v_mul_f32_e32 v73, v47, v47
	v_mul_f32_e32 v74, v49, v49
	v_fmac_f32_e32 v71, v54, v54
	v_fmac_f32_e32 v72, v56, v56
	v_add_f32_e32 v1, v1, v68
	v_add_f32_e32 v68, v69, v70
	v_fmac_f32_e32 v73, v46, v46
	v_fmac_f32_e32 v74, v48, v48
	v_add_f32_e32 v69, v71, v72
	s_waitcnt vmcnt(12)
	v_mul_f32_e32 v71, v51, v51
	v_mul_f32_e32 v72, v53, v53
	v_add_f32_e32 v1, v1, v68
	v_add_f32_e32 v70, v73, v74
	s_waitcnt vmcnt(11)
	v_mul_f32_e32 v73, v43, v43
	v_mul_f32_e32 v74, v45, v45
	v_fmac_f32_e32 v71, v50, v50
	v_fmac_f32_e32 v72, v52, v52
	v_add_f32_e32 v1, v1, v69
	s_waitcnt vmcnt(10)
	v_mul_f32_e32 v75, v39, v39
	v_mul_f32_e32 v76, v41, v41
	v_fmac_f32_e32 v73, v42, v42
	v_fmac_f32_e32 v74, v44, v44
	v_add_f32_e32 v68, v71, v72
	v_add_f32_e32 v1, v1, v70
	s_waitcnt vmcnt(9)
	v_mul_f32_e32 v77, v35, v35
	v_mul_f32_e32 v82, v37, v37
	v_fmac_f32_e32 v75, v38, v38
	v_fmac_f32_e32 v76, v40, v40
	v_add_f32_e32 v69, v73, v74
	v_add_f32_e32 v1, v1, v68
	s_waitcnt vmcnt(8)
	v_mul_f32_e32 v83, v31, v31
	v_mul_f32_e32 v84, v33, v33
	v_fmac_f32_e32 v77, v34, v34
	v_fmac_f32_e32 v82, v36, v36
	v_add_f32_e32 v71, v75, v76
	v_add_f32_e32 v1, v1, v69
	v_fmac_f32_e32 v83, v30, v30
	v_fmac_f32_e32 v84, v32, v32
	v_add_f32_e32 v72, v77, v82
	v_add_f32_e32 v1, v1, v71
	v_lshl_add_u64 v[70:71], s[54:55], 0, v[66:67]
	v_add_f32_e32 v73, v83, v84
	v_add_f32_e32 v1, v1, v72
	v_add_co_u32_e32 v72, vcc, s0, v70
	s_waitcnt vmcnt(7)
	v_mul_f32_e32 v85, v23, v23
	v_add_f32_e32 v1, v1, v73
	v_mul_f32_e32 v68, v25, v25
	v_addc_co_u32_e32 v73, vcc, 0, v71, vcc
	s_mov_b32 s0, 0x165000
	v_fmac_f32_e32 v85, v22, v22
	v_fmac_f32_e32 v68, v24, v24
	v_add_co_u32_e32 v74, vcc, s0, v70
	v_add_f32_e32 v68, v85, v68
	s_nop 0
	v_addc_co_u32_e32 v75, vcc, 0, v71, vcc
	global_load_dwordx4 v[82:85], v[72:73], off offset:-4096
	global_load_dwordx4 v[86:89], v[74:75], off offset:-4096
	v_add_f32_e32 v1, v1, v68
	s_waitcnt vmcnt(8)
	v_mul_f32_e32 v68, v19, v19
	v_mul_f32_e32 v69, v21, v21
	v_fmac_f32_e32 v68, v18, v18
	v_fmac_f32_e32 v69, v20, v20
	v_add_f32_e32 v68, v68, v69
	v_add_f32_e32 v1, v1, v68
	s_waitcnt vmcnt(7)
	v_mul_f32_e32 v68, v7, v7
	v_mul_f32_e32 v69, v9, v9
	v_fmac_f32_e32 v68, v6, v6
	v_fmac_f32_e32 v69, v8, v8
	v_add_f32_e32 v68, v68, v69
	v_add_f32_e32 v1, v1, v68
	s_waitcnt vmcnt(6)
	v_mul_f32_e32 v68, v3, v3
	v_mul_f32_e32 v69, v5, v5
	v_fmac_f32_e32 v68, v2, v2
	v_fmac_f32_e32 v69, v4, v4
	v_add_f32_e32 v68, v68, v69
	v_add_f32_e32 v1, v1, v68
	s_waitcnt vmcnt(4)
	v_mul_f32_e32 v68, v27, v27
	v_mul_f32_e32 v69, v29, v29
	v_fmac_f32_e32 v68, v26, v26
	v_fmac_f32_e32 v69, v28, v28
	v_add_f32_e32 v68, v68, v69
	v_add_f32_e32 v1, v1, v68
	s_waitcnt vmcnt(3)
	v_mul_f32_e32 v68, v15, v15
	v_mul_f32_e32 v69, v17, v17
	v_fmac_f32_e32 v68, v14, v14
	v_fmac_f32_e32 v69, v16, v16
	v_add_f32_e32 v68, v68, v69
	v_add_f32_e32 v1, v1, v68
	s_waitcnt vmcnt(2)
	v_mul_f32_e32 v68, v11, v11
	v_mul_f32_e32 v69, v13, v13
	v_fmac_f32_e32 v68, v10, v10
	v_fmac_f32_e32 v69, v12, v12
	v_add_f32_e32 v68, v68, v69
	v_add_f32_e32 v1, v1, v68
	s_nop 1
	v_add_f32_dpp v1, v1, v1 quad_perm:[1,0,3,2] row_mask:0xf bank_mask:0xf bound_ctrl:1
	s_nop 1
	v_add_f32_dpp v1, v1, v1 quad_perm:[2,3,0,1] row_mask:0xf bank_mask:0xf bound_ctrl:1
	s_nop 1
	v_add_f32_dpp v1, v1, v1 row_half_mirror row_mask:0xf bank_mask:0xf bound_ctrl:1
	s_nop 1
	v_add_f32_dpp v1, v1, v1 row_mirror row_mask:0xf bank_mask:0xf bound_ctrl:1
	ds_swizzle_b32 v68, v1 offset:swizzle(SWAP,16)
	s_waitcnt lgkmcnt(0)
	v_add_f32_e32 v1, v1, v68
	s_nop 0
	v_readlane_b32 s1, v1, 32
	v_readlane_b32 s0, v1, 0
	v_mov_b32_e32 v68, 0x358637bd
	v_mov_b32_e32 v1, s1
	v_add_f32_e32 v1, s0, v1
	v_fmac_f32_e32 v68, 0x39800000, v1
	s_mov_b32 s0, 0xf800000
	v_mul_f32_e32 v1, 0x4f800000, v68
	v_cmp_gt_f32_e32 vcc, s0, v68
	s_nop 1
	v_cndmask_b32_e32 v1, v68, v1, vcc
	v_sqrt_f32_e32 v68, v1
	s_nop 0
	v_add_u32_e32 v69, -1, v68
	v_fma_f32 v76, -v69, v68, v1
	v_cmp_ge_f32_e64 s[0:1], 0, v76
	v_add_u32_e32 v76, 1, v68
	s_nop 0
	v_cndmask_b32_e64 v69, v68, v69, s[0:1]
	v_fma_f32 v68, -v76, v68, v1
	v_cmp_lt_f32_e64 s[0:1], 0, v68
	s_nop 1
	v_cndmask_b32_e64 v68, v69, v76, s[0:1]
	v_mul_f32_e32 v69, 0x37800000, v68
	v_cndmask_b32_e32 v68, v68, v69, vcc
	v_mov_b32_e32 v69, 0x260
	v_cmp_class_f32_e32 vcc, v1, v69
	s_nop 1
	v_cndmask_b32_e32 v1, v68, v1, vcc
	v_div_scale_f32 v68, s[0:1], v1, v1, 1.0
	v_rcp_f32_e32 v69, v68
	s_lshl_b64 s[0:1], s[2:3], 13
	s_add_u32 s0, s22, s0
	s_addc_u32 s1, s23, s1
	v_fma_f32 v76, -v68, v69, 1.0
	v_fmac_f32_e32 v69, v76, v69
	v_div_scale_f32 v76, vcc, 1.0, v1, 1.0
	v_mul_f32_e32 v77, v76, v69
	v_fma_f32 v90, -v68, v77, v76
	v_fmac_f32_e32 v77, v90, v69
	v_fma_f32 v68, -v68, v77, v76
	v_div_fmas_f32 v68, v68, v69, v77
	v_div_fixup_f32 v68, v68, v1, 1.0
	v_pk_mul_f32 v[64:65], v[64:65], v[68:69] op_sel_hi:[1,0]
	v_pk_mul_f32 v[62:63], v[62:63], v[68:69] op_sel_hi:[1,0]
	v_pk_mul_f32 v[64:65], v[80:81], v[64:65]
	v_pk_mul_f32 v[62:63], v[78:79], v[62:63]
	s_waitcnt vmcnt(0)
	v_pk_add_f32 v[78:79], v[88:89], 1.0 op_sel_hi:[1,0]
	v_pk_add_f32 v[80:81], v[86:87], 1.0 op_sel_hi:[1,0]
	v_pk_fma_f32 v[64:65], v[78:79], v[64:65], v[84:85]
	v_pk_fma_f32 v[62:63], v[80:81], v[62:63], v[82:83]
	v_lshlrev_b32_e32 v76, 3, v178
	v_cvt_pk_bf16_f32 v62, v62, v63
	v_cvt_pk_bf16_f32 v63, v64, v65
	s_mov_b64 s[2:3], 0x160000
	global_store_dwordx2 v76, v[62:63], s[0:1]
	s_mov_b64 s[2:3], 0x1000
	v_add_u32_e32 v240, 0x1000, v66
	v_add_u32_e32 v241, 0x2000, v66
	v_add_u32_e32 v242, 0x3000, v66
	v_lshl_add_u64 v[244:245], v[74:75], 0, s[2:3]
	v_lshl_add_u64 v[246:247], v[244:245], 0, s[2:3]
	v_lshl_add_u64 v[248:249], v[72:73], 0, s[2:3]
	v_lshl_add_u64 v[250:251], v[248:249], 0, s[2:3]
	v_add_u32_e32 v252, 0x1000, v76
	global_load_dwordx4 v[100:103], v66, s[28:29] offset:1024
	global_load_dwordx4 v[104:107], v[74:75], off offset:-3072
	global_load_dwordx4 v[108:111], v[72:73], off offset:-3072
	global_load_dwordx4 v[112:115], v66, s[28:29] offset:2048
	global_load_dwordx4 v[116:119], v[74:75], off offset:-2048
	global_load_dwordx4 v[120:123], v[72:73], off offset:-2048
	global_load_dwordx4 v[124:127], v66, s[28:29] offset:3072
	global_load_dwordx4 v[128:131], v[74:75], off offset:-1024
	global_load_dwordx4 v[132:135], v[72:73], off offset:-1024
	global_load_dwordx4 v[136:139], v240, s[28:29]
	global_load_dwordx4 v[140:143], v[74:75], off
	global_load_dwordx4 v[144:147], v[72:73], off
	global_load_dwordx4 v[148:151], v240, s[28:29] offset:1024
	global_load_dwordx4 v[152:155], v[74:75], off offset:1024
	global_load_dwordx4 v[156:159], v[72:73], off offset:1024
	global_load_dwordx4 v[180:183], v240, s[28:29] offset:2048
	global_load_dwordx4 v[184:187], v[74:75], off offset:2048
	global_load_dwordx4 v[188:191], v[72:73], off offset:2048
	global_load_dwordx4 v[192:195], v240, s[28:29] offset:3072
	global_load_dwordx4 v[196:199], v[74:75], off offset:3072
	global_load_dwordx4 v[200:203], v[72:73], off offset:3072
	global_load_dwordx4 v[204:207], v241, s[28:29]
	global_load_dwordx4 v[208:211], v[244:245], off
	global_load_dwordx4 v[212:215], v[248:249], off
	global_load_dwordx4 v[216:219], v241, s[28:29] offset:1024
	global_load_dwordx4 v[220:223], v[244:245], off offset:1024
	global_load_dwordx4 v[224:227], v[248:249], off offset:1024
	global_load_dwordx4 v[228:231], v241, s[28:29] offset:2048
	global_load_dwordx4 v[232:235], v[244:245], off offset:2048
	global_load_dwordx4 v[236:239], v[248:249], off offset:2048
	v_pk_mul_f32 v[60:61], v[60:61], v[68:69] op_sel_hi:[1,0]
	v_pk_mul_f32 v[58:59], v[58:59], v[68:69] op_sel_hi:[1,0]
	v_pk_mul_f32 v[56:57], v[56:57], v[68:69] op_sel_hi:[1,0]
	v_pk_mul_f32 v[54:55], v[54:55], v[68:69] op_sel_hi:[1,0]
	v_pk_mul_f32 v[48:49], v[48:49], v[68:69] op_sel_hi:[1,0]
	v_pk_mul_f32 v[46:47], v[46:47], v[68:69] op_sel_hi:[1,0]
	v_pk_mul_f32 v[52:53], v[52:53], v[68:69] op_sel_hi:[1,0]
	v_pk_mul_f32 v[50:51], v[50:51], v[68:69] op_sel_hi:[1,0]
	v_pk_mul_f32 v[44:45], v[44:45], v[68:69] op_sel_hi:[1,0]
	v_pk_mul_f32 v[42:43], v[42:43], v[68:69] op_sel_hi:[1,0]
	v_pk_mul_f32 v[40:41], v[40:41], v[68:69] op_sel_hi:[1,0]
	v_pk_mul_f32 v[38:39], v[38:39], v[68:69] op_sel_hi:[1,0]
	v_pk_mul_f32 v[36:37], v[36:37], v[68:69] op_sel_hi:[1,0]
	v_pk_mul_f32 v[34:35], v[34:35], v[68:69] op_sel_hi:[1,0]
	v_pk_mul_f32 v[32:33], v[32:33], v[68:69] op_sel_hi:[1,0]
	v_pk_mul_f32 v[30:31], v[30:31], v[68:69] op_sel_hi:[1,0]
	v_pk_mul_f32 v[24:25], v[24:25], v[68:69] op_sel_hi:[1,0]
	v_pk_mul_f32 v[22:23], v[22:23], v[68:69] op_sel_hi:[1,0]
	v_pk_mul_f32 v[20:21], v[20:21], v[68:69] op_sel_hi:[1,0]
	v_pk_mul_f32 v[18:19], v[18:19], v[68:69] op_sel_hi:[1,0]
	v_pk_mul_f32 v[8:9], v[8:9], v[68:69] op_sel_hi:[1,0]
	v_pk_mul_f32 v[6:7], v[6:7], v[68:69] op_sel_hi:[1,0]
	v_pk_mul_f32 v[4:5], v[4:5], v[68:69] op_sel_hi:[1,0]
	v_pk_mul_f32 v[2:3], v[2:3], v[68:69] op_sel_hi:[1,0]
	v_pk_mul_f32 v[16:17], v[16:17], v[68:69] op_sel_hi:[1,0]
	v_pk_mul_f32 v[14:15], v[14:15], v[68:69] op_sel_hi:[1,0]
	v_pk_mul_f32 v[12:13], v[12:13], v[68:69] op_sel_hi:[1,0]
	v_pk_mul_f32 v[10:11], v[10:11], v[68:69] op_sel_hi:[1,0]
	v_pk_mul_f32 v[94:95], v[28:29], v[68:69] op_sel_hi:[1,0]
	v_pk_mul_f32 v[92:93], v[26:27], v[68:69] op_sel_hi:[1,0]
	s_waitcnt vmcnt(15)
	v_pk_mul_f32 v[58:59], v[100:101], v[58:59]
	v_pk_mul_f32 v[60:61], v[102:103], v[60:61]
	v_pk_add_f32 v[106:107], v[106:107], 1.0 op_sel_hi:[1,0]
	v_pk_add_f32 v[104:105], v[104:105], 1.0 op_sel_hi:[1,0]
	s_nop 0
	v_pk_fma_f32 v[60:61], v[60:61], v[106:107], v[110:111]
	v_pk_fma_f32 v[58:59], v[58:59], v[104:105], v[108:109]
	s_nop 0
	v_cvt_pk_bf16_f32 v58, v58, v59
	v_cvt_pk_bf16_f32 v59, v60, v61
	global_store_dwordx2 v76, v[58:59], s[0:1] offset:512
	v_pk_mul_f32 v[54:55], v[112:113], v[54:55]
	v_pk_mul_f32 v[56:57], v[114:115], v[56:57]
	v_pk_add_f32 v[118:119], v[118:119], 1.0 op_sel_hi:[1,0]
	v_pk_add_f32 v[116:117], v[116:117], 1.0 op_sel_hi:[1,0]
	s_nop 0
	v_pk_fma_f32 v[56:57], v[56:57], v[118:119], v[122:123]
	v_pk_fma_f32 v[54:55], v[54:55], v[116:117], v[120:121]
	s_nop 0
	v_cvt_pk_bf16_f32 v54, v54, v55
	v_cvt_pk_bf16_f32 v55, v56, v57
	global_store_dwordx2 v76, v[54:55], s[0:1] offset:1024
	v_pk_mul_f32 v[46:47], v[124:125], v[46:47]
	v_pk_mul_f32 v[48:49], v[126:127], v[48:49]
	v_pk_add_f32 v[130:131], v[130:131], 1.0 op_sel_hi:[1,0]
	v_pk_add_f32 v[128:129], v[128:129], 1.0 op_sel_hi:[1,0]
	s_nop 0
	v_pk_fma_f32 v[48:49], v[48:49], v[130:131], v[134:135]
	v_pk_fma_f32 v[46:47], v[46:47], v[128:129], v[132:133]
	s_nop 0
	v_cvt_pk_bf16_f32 v46, v46, v47
	v_cvt_pk_bf16_f32 v47, v48, v49
	global_store_dwordx2 v76, v[46:47], s[0:1] offset:1536
	v_pk_mul_f32 v[50:51], v[136:137], v[50:51]
	v_pk_mul_f32 v[52:53], v[138:139], v[52:53]
	v_pk_add_f32 v[142:143], v[142:143], 1.0 op_sel_hi:[1,0]
	v_pk_add_f32 v[140:141], v[140:141], 1.0 op_sel_hi:[1,0]
	s_nop 0
	v_pk_fma_f32 v[52:53], v[52:53], v[142:143], v[146:147]
	v_pk_fma_f32 v[50:51], v[50:51], v[140:141], v[144:145]
	s_nop 0
	v_cvt_pk_bf16_f32 v50, v50, v51
	v_cvt_pk_bf16_f32 v51, v52, v53
	global_store_dwordx2 v76, v[50:51], s[0:1] offset:2048
	v_pk_mul_f32 v[42:43], v[148:149], v[42:43]
	v_pk_mul_f32 v[44:45], v[150:151], v[44:45]
	v_pk_add_f32 v[154:155], v[154:155], 1.0 op_sel_hi:[1,0]
	v_pk_add_f32 v[152:153], v[152:153], 1.0 op_sel_hi:[1,0]
	s_nop 0
	v_pk_fma_f32 v[44:45], v[44:45], v[154:155], v[158:159]
	v_pk_fma_f32 v[42:43], v[42:43], v[152:153], v[156:157]
	s_nop 0
	v_cvt_pk_bf16_f32 v42, v42, v43
	v_cvt_pk_bf16_f32 v43, v44, v45
	global_store_dwordx2 v76, v[42:43], s[0:1] offset:2560
	global_load_dwordx4 v[100:103], v241, s[28:29] offset:3072
	global_load_dwordx4 v[104:107], v[244:245], off offset:3072
	global_load_dwordx4 v[108:111], v[248:249], off offset:3072
	global_load_dwordx4 v[112:115], v242, s[28:29]
	global_load_dwordx4 v[116:119], v[246:247], off
	global_load_dwordx4 v[120:123], v[250:251], off
	global_load_dwordx4 v[124:127], v242, s[28:29] offset:1024
	global_load_dwordx4 v[128:131], v[246:247], off offset:1024
	global_load_dwordx4 v[132:135], v[250:251], off offset:1024
	global_load_dwordx4 v[136:139], v242, s[28:29] offset:2048
	global_load_dwordx4 v[140:143], v[246:247], off offset:2048
	global_load_dwordx4 v[144:147], v[250:251], off offset:2048
	global_load_dwordx4 v[148:151], v242, s[28:29] offset:3072
	global_load_dwordx4 v[152:155], v[246:247], off offset:3072
	global_load_dwordx4 v[156:159], v[250:251], off offset:3072
	s_waitcnt vmcnt(20)
	v_pk_mul_f32 v[38:39], v[180:181], v[38:39]
	v_pk_mul_f32 v[40:41], v[182:183], v[40:41]
	v_pk_add_f32 v[186:187], v[186:187], 1.0 op_sel_hi:[1,0]
	v_pk_add_f32 v[184:185], v[184:185], 1.0 op_sel_hi:[1,0]
	s_nop 0
	v_pk_fma_f32 v[40:41], v[40:41], v[186:187], v[190:191]
	v_pk_fma_f32 v[38:39], v[38:39], v[184:185], v[188:189]
	s_nop 0
	v_cvt_pk_bf16_f32 v38, v38, v39
	v_cvt_pk_bf16_f32 v39, v40, v41
	global_store_dwordx2 v76, v[38:39], s[0:1] offset:3072
	v_pk_mul_f32 v[34:35], v[192:193], v[34:35]
	v_pk_mul_f32 v[36:37], v[194:195], v[36:37]
	v_pk_add_f32 v[198:199], v[198:199], 1.0 op_sel_hi:[1,0]
	v_pk_add_f32 v[196:197], v[196:197], 1.0 op_sel_hi:[1,0]
	s_nop 0
	v_pk_fma_f32 v[36:37], v[36:37], v[198:199], v[202:203]
	v_pk_fma_f32 v[34:35], v[34:35], v[196:197], v[200:201]
	s_nop 0
	v_cvt_pk_bf16_f32 v34, v34, v35
	v_cvt_pk_bf16_f32 v35, v36, v37
	global_store_dwordx2 v76, v[34:35], s[0:1] offset:3584
	v_pk_mul_f32 v[30:31], v[204:205], v[30:31]
	v_pk_mul_f32 v[32:33], v[206:207], v[32:33]
	v_pk_add_f32 v[210:211], v[210:211], 1.0 op_sel_hi:[1,0]
	v_pk_add_f32 v[208:209], v[208:209], 1.0 op_sel_hi:[1,0]
	s_nop 0
	v_pk_fma_f32 v[32:33], v[32:33], v[210:211], v[214:215]
	v_pk_fma_f32 v[30:31], v[30:31], v[208:209], v[212:213]
	s_nop 0
	v_cvt_pk_bf16_f32 v30, v30, v31
	v_cvt_pk_bf16_f32 v31, v32, v33
	global_store_dwordx2 v252, v[30:31], s[0:1]
	v_pk_mul_f32 v[22:23], v[216:217], v[22:23]
	v_pk_mul_f32 v[24:25], v[218:219], v[24:25]
	v_pk_add_f32 v[222:223], v[222:223], 1.0 op_sel_hi:[1,0]
	v_pk_add_f32 v[220:221], v[220:221], 1.0 op_sel_hi:[1,0]
	s_nop 0
	v_pk_fma_f32 v[24:25], v[24:25], v[222:223], v[226:227]
	v_pk_fma_f32 v[22:23], v[22:23], v[220:221], v[224:225]
	s_nop 0
	v_cvt_pk_bf16_f32 v22, v22, v23
	v_cvt_pk_bf16_f32 v23, v24, v25
	global_store_dwordx2 v252, v[22:23], s[0:1] offset:512
	v_pk_mul_f32 v[18:19], v[228:229], v[18:19]
	v_pk_mul_f32 v[20:21], v[230:231], v[20:21]
	v_pk_add_f32 v[234:235], v[234:235], 1.0 op_sel_hi:[1,0]
	v_pk_add_f32 v[232:233], v[232:233], 1.0 op_sel_hi:[1,0]
	s_nop 0
	v_pk_fma_f32 v[20:21], v[20:21], v[234:235], v[238:239]
	v_pk_fma_f32 v[18:19], v[18:19], v[232:233], v[236:237]
	s_nop 0
	v_cvt_pk_bf16_f32 v18, v18, v19
	v_cvt_pk_bf16_f32 v19, v20, v21
	global_store_dwordx2 v252, v[18:19], s[0:1] offset:1024
	s_waitcnt vmcnt(5)
	v_pk_mul_f32 v[6:7], v[100:101], v[6:7]
	v_pk_mul_f32 v[8:9], v[102:103], v[8:9]
	v_pk_add_f32 v[106:107], v[106:107], 1.0 op_sel_hi:[1,0]
	v_pk_add_f32 v[104:105], v[104:105], 1.0 op_sel_hi:[1,0]
	s_nop 0
	v_pk_fma_f32 v[8:9], v[8:9], v[106:107], v[110:111]
	v_pk_fma_f32 v[6:7], v[6:7], v[104:105], v[108:109]
	s_nop 0
	v_cvt_pk_bf16_f32 v6, v6, v7
	v_cvt_pk_bf16_f32 v7, v8, v9
	global_store_dwordx2 v252, v[6:7], s[0:1] offset:1536
	v_pk_mul_f32 v[2:3], v[112:113], v[2:3]
	v_pk_mul_f32 v[4:5], v[114:115], v[4:5]
	v_pk_add_f32 v[118:119], v[118:119], 1.0 op_sel_hi:[1,0]
	v_pk_add_f32 v[116:117], v[116:117], 1.0 op_sel_hi:[1,0]
	s_nop 0
	v_pk_fma_f32 v[4:5], v[4:5], v[118:119], v[122:123]
	v_pk_fma_f32 v[2:3], v[2:3], v[116:117], v[120:121]
	s_nop 0
	v_cvt_pk_bf16_f32 v2, v2, v3
	v_cvt_pk_bf16_f32 v3, v4, v5
	global_store_dwordx2 v252, v[2:3], s[0:1] offset:2048
	v_pk_mul_f32 v[92:93], v[124:125], v[92:93]
	v_pk_mul_f32 v[94:95], v[126:127], v[94:95]
	v_pk_add_f32 v[130:131], v[130:131], 1.0 op_sel_hi:[1,0]
	v_pk_add_f32 v[128:129], v[128:129], 1.0 op_sel_hi:[1,0]
	s_nop 0
	v_pk_fma_f32 v[94:95], v[94:95], v[130:131], v[134:135]
	v_pk_fma_f32 v[92:93], v[92:93], v[128:129], v[132:133]
	s_nop 0
	v_cvt_pk_bf16_f32 v92, v92, v93
	v_cvt_pk_bf16_f32 v93, v94, v95
	global_store_dwordx2 v252, v[92:93], s[0:1] offset:2560
	v_pk_mul_f32 v[14:15], v[136:137], v[14:15]
	v_pk_mul_f32 v[16:17], v[138:139], v[16:17]
	v_pk_add_f32 v[142:143], v[142:143], 1.0 op_sel_hi:[1,0]
	v_pk_add_f32 v[140:141], v[140:141], 1.0 op_sel_hi:[1,0]
	s_nop 0
	v_pk_fma_f32 v[16:17], v[16:17], v[142:143], v[146:147]
	v_pk_fma_f32 v[14:15], v[14:15], v[140:141], v[144:145]
	s_nop 0
	v_cvt_pk_bf16_f32 v14, v14, v15
	v_cvt_pk_bf16_f32 v15, v16, v17
	global_store_dwordx2 v252, v[14:15], s[0:1] offset:3072
	v_pk_mul_f32 v[10:11], v[148:149], v[10:11]
	v_pk_mul_f32 v[12:13], v[150:151], v[12:13]
	v_pk_add_f32 v[154:155], v[154:155], 1.0 op_sel_hi:[1,0]
	v_pk_add_f32 v[152:153], v[152:153], 1.0 op_sel_hi:[1,0]
	s_nop 0
	v_pk_fma_f32 v[12:13], v[12:13], v[154:155], v[158:159]
	v_pk_fma_f32 v[10:11], v[10:11], v[152:153], v[156:157]
	s_nop 0
	v_cvt_pk_bf16_f32 v10, v10, v11
	v_cvt_pk_bf16_f32 v11, v12, v13
	global_store_dwordx2 v252, v[10:11], s[0:1] offset:3584
